# adds post phase: loop-invariant per-head norm gammas preloaded once, in-loop reloads and their store-ack waits removed
# baseline (speedup 1.0000x reference)
.LBB0_719:
	s_or_b64 exec, exec, s[10:11]
	s_mov_b64 s[10:11], s[76:77]
	s_waitcnt lgkmcnt(0)
	v_mov_b32_e32 v0, v172
	s_barrier
	v_readlane_b32 s1, v241, 4
	v_readfirstlane_b32 s0, v0
	s_ashr_i32 s0, s0, 6
	s_add_i32 s12, s0, s1
	s_cmpk_gt_i32 s12, 0x2fff
	s_cbranch_scc1 .LBB0_722
	v_cmp_lt_i32_e32 vcc, v176, v174
	s_load_dwordx2 s[4:5], s[10:11], 0xa8
	s_load_dwordx2 s[8:9], s[10:11], 0x68
	s_nop 0
	s_load_dwordx2 s[10:11], s[10:11], 0x78
	v_cndmask_b32_e32 v1, v173, v176, vcc
	v_cmp_lt_i32_e32 vcc, v175, v174
	v_lshlrev_b32_e32 v58, 2, v1
	s_lshl_b32 s14, s60, 7
	v_cndmask_b32_e32 v1, v173, v175, vcc
	v_lshlrev_b32_e32 v59, 2, v1
	v_xor_b32_e32 v1, 4, v173
	v_cmp_lt_i32_e32 vcc, v1, v174
	s_mov_b32 s15, s59
	s_lshl_b32 s58, s60, 8
	v_cndmask_b32_e32 v1, v173, v1, vcc
	v_lshlrev_b32_e32 v60, 2, v1
	v_xor_b32_e32 v1, 8, v173
	s_lshl_b64 s[14:15], s[14:15], 2
	v_cmp_lt_i32_e32 vcc, v1, v174
	s_waitcnt lgkmcnt(0)
	s_add_u32 s10, s10, s14
	s_addc_u32 s11, s11, s15
	v_cndmask_b32_e32 v1, v173, v1, vcc
	s_lshl_b64 s[14:15], s[58:59], 2
	v_lshlrev_b32_e32 v61, 2, v1
	v_lshlrev_b32_e32 v1, 5, v0
	s_add_u32 s8, s8, s14
	v_and_b32_e32 v144, 0x1e0, v1
	v_xor_b32_e32 v2, 16, v173
	s_addc_u32 s9, s9, s15
	v_lshl_add_u64 v[8:9], s[10:11], 0, v[144:145]
	v_cmp_lt_i32_e32 vcc, v2, v174
	v_and_b32_e32 v144, 0x3e0, v1
	v_lshlrev_b32_e32 v1, 4, v0
	v_cndmask_b32_e32 v2, v173, v2, vcc
	v_lshl_add_u64 v[10:11], s[8:9], 0, v[144:145]
	v_and_b32_e32 v144, 0x3f0, v1
	s_waitcnt vmcnt(0)
	v_lshlrev_b32_e32 v62, 2, v2
	v_lshl_add_u64 v[2:3], s[4:5], 0, v[144:145]
	s_mov_b64 s[8:9], 0xd400000
	s_ashr_i32 s13, s12, 31
	v_lshl_add_u64 v[12:13], v[2:3], 0, s[8:9]
	s_lshl_b64 s[8:9], s[12:13], 14
	s_add_u32 s14, s4, s8
	s_addc_u32 s15, s5, s9
	s_lshl_b64 s[8:9], s[12:13], 12
	s_add_u32 s16, s4, s8
	v_and_b32_e32 v0, 63, v0
	s_addc_u32 s17, s5, s9
	s_lshl_b32 s0, s0, 6
	v_readlane_b32 s1, v241, 5
	v_lshlrev_b32_e32 v144, 4, v0
	s_add_i32 s4, s1, s0
	s_mov_b32 s13, 0x25400000
	global_load_dwordx4 v[100:103], v[10:11], off offset:16
	global_load_dwordx4 v[104:107], v[10:11], off
	global_load_dwordx4 v[108:111], v[8:9], off offset:16
	global_load_dwordx4 v[112:115], v[8:9], off
	s_waitcnt vmcnt(0)
.LBB0_721:
	s_cmpk_gt_i32 s12, 0xfff
	s_cselect_b64 s[0:1], -1, 0
	s_and_b32 s8, s12, 0x7ffff000
	s_and_b32 s9, s4, 0xfc0
	s_bfe_u32 s5, s12, 0x60006
	s_or_b32 s8, s9, s8
	s_and_b64 s[0:1], s[6:7], s[0:1]
	s_or_b32 s5, s8, s5
	s_and_b64 s[0:1], s[0:1], exec
	s_cselect_b32 s0, s5, s12
	v_lshl_add_u64 v[0:1], s[16:17], 0, v[144:145]
	s_ashr_i32 s1, s0, 31
	v_add_co_u32_e32 v20, vcc, s13, v0
	s_lshl_b64 s[10:11], s[0:1], 12
	s_nop 0
	v_addc_co_u32_e32 v21, vcc, 0, v1, vcc
	s_mov_b32 s0, 0x28400000
	v_add_co_u32_e32 v22, vcc, s0, v0
	v_lshl_add_u64 v[18:19], s[14:15], 0, v[144:145]
	s_nop 0
	v_addc_co_u32_e32 v23, vcc, 0, v1, vcc
	s_mov_b32 s0, 0x10401000
	global_load_dwordx4 v[14:17], v[20:21], off
	global_load_dwordx4 v[28:31], v[22:23], off
	v_add_co_u32_e32 v44, vcc, s0, v18
	s_mov_b32 s0, 0x358637bd
	s_nop 0
	v_addc_co_u32_e32 v45, vcc, 0, v19, vcc
	global_load_dwordx4 v[40:43], v[44:45], off
	global_load_dwordx4 v[52:55], v[20:21], off offset:1024
	global_load_dwordx4 v[64:67], v[22:23], off offset:1024
	global_load_dwordx4 v[68:71], v[44:45], off offset:1024
	s_add_i32 s12, s12, s34
	s_add_u32 s14, s14, s92
	s_addc_u32 s15, s15, s93
	s_add_u32 s16, s16, s42
	s_addc_u32 s17, s17, s43
	s_add_i32 s4, s4, s3
	s_cmpk_lt_i32 s12, 0x3000
	s_waitcnt vmcnt(5)
	v_lshlrev_b32_e32 v24, 16, v17
	v_and_b32_e32 v25, 0xffff0000, v17
	s_waitcnt vmcnt(4)
	v_lshlrev_b32_e32 v26, 16, v31
	v_and_b32_e32 v27, 0xffff0000, v31
	v_lshlrev_b32_e32 v32, 16, v16
	v_and_b32_e32 v33, 0xffff0000, v16
	v_lshlrev_b32_e32 v16, 16, v30
	v_and_b32_e32 v17, 0xffff0000, v30
	v_lshlrev_b32_e32 v30, 16, v15
	v_and_b32_e32 v31, 0xffff0000, v15
	v_lshlrev_b32_e32 v36, 16, v29
	v_and_b32_e32 v37, 0xffff0000, v29
	v_pk_add_f32 v[38:39], v[30:31], v[36:37]
	s_waitcnt vmcnt(3)
	v_lshlrev_b32_e32 v36, 16, v41
	v_and_b32_e32 v37, 0xffff0000, v41
	v_lshlrev_b32_e32 v30, 16, v14
	v_and_b32_e32 v31, 0xffff0000, v14
	v_lshlrev_b32_e32 v14, 16, v28
	v_and_b32_e32 v15, 0xffff0000, v28
	v_lshlrev_b32_e32 v48, 16, v40
	v_and_b32_e32 v49, 0xffff0000, v40
	s_waitcnt vmcnt(2)
	v_lshlrev_b32_e32 v28, 16, v55
	v_and_b32_e32 v29, 0xffff0000, v55
	v_lshlrev_b32_e32 v40, 16, v54
	v_and_b32_e32 v41, 0xffff0000, v54
	v_lshlrev_b32_e32 v44, 16, v53
	v_and_b32_e32 v45, 0xffff0000, v53
	v_lshlrev_b32_e32 v54, 16, v52
	v_and_b32_e32 v55, 0xffff0000, v52
	s_waitcnt vmcnt(1)
	v_lshlrev_b32_e32 v52, 16, v64
	v_and_b32_e32 v53, 0xffff0000, v64
	v_pk_add_f32 v[50:51], v[30:31], v[14:15]
	v_lshlrev_b32_e32 v46, 16, v65
	v_and_b32_e32 v47, 0xffff0000, v65
	v_pk_add_f32 v[54:55], v[54:55], v[52:53]
	v_pk_add_f32 v[26:27], v[24:25], v[26:27]
	v_lshlrev_b32_e32 v24, 16, v43
	v_and_b32_e32 v25, 0xffff0000, v43
	v_pk_add_f32 v[34:35], v[32:33], v[16:17]
	v_lshlrev_b32_e32 v32, 16, v42
	v_and_b32_e32 v33, 0xffff0000, v42
	v_lshlrev_b32_e32 v30, 16, v67
	v_and_b32_e32 v31, 0xffff0000, v67
	v_lshlrev_b32_e32 v42, 16, v66
	v_and_b32_e32 v43, 0xffff0000, v66
	v_pk_add_f32 v[46:47], v[44:45], v[46:47]
	s_waitcnt vmcnt(0)
	v_lshlrev_b32_e32 v44, 16, v69
	v_and_b32_e32 v45, 0xffff0000, v69
	v_lshlrev_b32_e32 v52, 16, v68
	v_and_b32_e32 v53, 0xffff0000, v68
	v_mov_b32_e32 v68, v55
	v_mov_b32_e32 v69, v51
	v_pk_mul_f32 v[72:73], v[38:39], v[38:39]
	v_pk_add_f32 v[30:31], v[28:29], v[30:31]
	v_lshlrev_b32_e32 v28, 16, v71
	v_and_b32_e32 v29, 0xffff0000, v71
	v_pk_add_f32 v[42:43], v[40:41], v[42:43]
	v_lshlrev_b32_e32 v40, 16, v70
	v_and_b32_e32 v41, 0xffff0000, v70
	v_pk_mul_f32 v[70:71], v[46:47], v[46:47]
	v_mov_b32_e32 v64, v54
	v_mov_b32_e32 v65, v50
	v_pk_mul_f32 v[68:69], v[68:69], v[68:69]
	v_pk_mul_f32 v[16:17], v[34:35], v[34:35]
	v_pk_fma_f32 v[64:65], v[64:65], v[64:65], v[68:69]
	v_mov_b32_e32 v68, v70
	v_mov_b32_e32 v69, v72
	v_pk_mul_f32 v[66:67], v[42:43], v[42:43]
	v_pk_add_f32 v[64:65], v[68:69], v[64:65]
	v_mov_b32_e32 v72, v71
	v_pk_add_f32 v[64:65], v[72:73], v[64:65]
	v_mov_b32_e32 v68, v66
	v_mov_b32_e32 v69, v16
	v_pk_mul_f32 v[56:57], v[26:27], v[26:27]
	v_pk_mul_f32 v[74:75], v[30:31], v[30:31]
	v_pk_add_f32 v[64:65], v[68:69], v[64:65]
	v_mov_b32_e32 v16, v67
	v_pk_add_f32 v[16:17], v[16:17], v[64:65]
	v_mov_b32_e32 v64, v74
	v_mov_b32_e32 v65, v56
	v_pk_add_f32 v[16:17], v[64:65], v[16:17]
	v_mov_b32_e32 v56, v75
	v_pk_add_f32 v[16:17], v[56:57], v[16:17]
	ds_bpermute_b32 v57, v58, v17
	ds_bpermute_b32 v56, v58, v16
	v_lshl_add_u64 v[14:15], v[12:13], 0, s[10:11]
	s_waitcnt lgkmcnt(0)
	v_pk_add_f32 v[16:17], v[16:17], v[56:57]
	ds_bpermute_b32 v57, v59, v17
	ds_bpermute_b32 v56, v59, v16
	s_waitcnt lgkmcnt(0)
	v_pk_add_f32 v[16:17], v[16:17], v[56:57]
	ds_bpermute_b32 v57, v60, v17
	ds_bpermute_b32 v56, v60, v16
	s_waitcnt lgkmcnt(0)
	v_pk_add_f32 v[16:17], v[16:17], v[56:57]
	ds_bpermute_b32 v57, v61, v17
	ds_bpermute_b32 v56, v61, v16
	s_waitcnt lgkmcnt(0)
	v_pk_add_f32 v[16:17], v[16:17], v[56:57]
	ds_bpermute_b32 v57, v62, v17
	ds_bpermute_b32 v56, v62, v16
	s_waitcnt lgkmcnt(0)
	v_pk_add_f32 v[56:57], v[16:17], v[56:57]
	v_mov_b64_e32 v[16:17], s[0:1]
	s_mov_b32 s0, 0x3b800000
	v_pk_fma_f32 v[56:57], v[56:57], s[0:1], v[16:17] op_sel_hi:[1,0,0]
	s_mov_b32 s0, 0x10403000
	v_mul_f32_e32 v63, 0x4b800000, v57
	v_cmp_gt_f32_e64 s[10:11], s72, v57
	v_cmp_gt_f32_e32 vcc, s72, v56
	s_nop 0
	v_cndmask_b32_e64 v57, v57, v63, s[10:11]
	v_rsq_f32_e32 v57, v57
	s_nop 0
	v_mul_f32_e32 v63, 0x45800000, v57
	v_cndmask_b32_e64 v64, v57, v63, s[10:11]
	v_pk_mul_f32 v[34:35], v[34:35], v[64:65] op_sel_hi:[1,0]
	v_pk_mul_f32 v[50:51], v[50:51], v[64:65] op_sel_hi:[1,0]
	v_pk_mul_f32 v[0:1], v[100:101], v[34:35]
	v_pk_mul_f32 v[4:5], v[104:105], v[50:51]
	v_pk_mul_f32 v[32:33], v[0:1], v[32:33]
	v_pk_mul_f32 v[0:1], v[38:39], v[64:65] op_sel_hi:[1,0]
	v_pk_mul_f32 v[4:5], v[4:5], v[48:49]
	v_pk_mul_f32 v[0:1], v[106:107], v[0:1]
	s_brev_b32 s10, 60
	v_pk_mul_f32 v[6:7], v[0:1], v[36:37]
	v_pk_mul_f32 v[0:1], v[26:27], v[64:65] op_sel_hi:[1,0]
	s_nop 0
	v_pk_mul_f32 v[0:1], v[102:103], v[0:1]
	v_cvt_pk_bf16_f32 v2, v32, v33
	v_pk_mul_f32 v[24:25], v[0:1], v[24:25]
	v_cvt_pk_bf16_f32 v0, v4, v5
	v_cvt_pk_bf16_f32 v1, v6, v7
	v_cvt_pk_bf16_f32 v3, v24, v25
	global_store_dwordx4 v[14:15], v[0:3], off
	s_nop 0
	v_mul_f32_e32 v24, 0x4b800000, v56
	v_cndmask_b32_e32 v24, v56, v24, vcc
	v_rsq_f32_e32 v24, v24
	s_nop 0
	v_mul_f32_e32 v25, 0x45800000, v24
	v_cndmask_b32_e32 v24, v24, v25, vcc
	v_pk_mul_f32 v[26:27], v[54:55], v[24:25] op_sel_hi:[1,0]
	v_add_co_u32_e32 v54, vcc, s0, v18
	v_pk_mul_f32 v[4:5], v[104:105], v[26:27]
	v_pk_mul_f32 v[26:27], v[42:43], v[24:25] op_sel_hi:[1,0]
	v_pk_mul_f32 v[4:5], v[4:5], v[52:53]
	v_pk_mul_f32 v[0:1], v[100:101], v[26:27]
	v_addc_co_u32_e32 v55, vcc, 0, v19, vcc
	v_pk_mul_f32 v[26:27], v[0:1], v[40:41]
	v_pk_mul_f32 v[0:1], v[46:47], v[24:25] op_sel_hi:[1,0]
	s_nop 0
	v_pk_mul_f32 v[0:1], v[106:107], v[0:1]
	s_nop 0
	v_pk_mul_f32 v[6:7], v[0:1], v[44:45]
	v_pk_mul_f32 v[0:1], v[30:31], v[24:25] op_sel_hi:[1,0]
	s_nop 0
	v_pk_mul_f32 v[0:1], v[102:103], v[0:1]
	v_cvt_pk_bf16_f32 v2, v26, v27
	v_pk_mul_f32 v[24:25], v[0:1], v[28:29]
	v_cvt_pk_bf16_f32 v0, v4, v5
	v_cvt_pk_bf16_f32 v1, v6, v7
	v_cvt_pk_bf16_f32 v3, v24, v25
	global_store_dwordx4 v[14:15], v[0:3], off offset:1024
	global_load_dwordx4 v[24:27], v[20:21], off offset:2048
	global_load_dwordx4 v[28:31], v[22:23], off offset:2048
	global_load_dwordx4 v[34:37], v[54:55], off offset:2048
	s_nop 0
	s_waitcnt vmcnt(2)
	v_lshlrev_b32_e32 v18, 16, v27
	v_and_b32_e32 v19, 0xffff0000, v27
	s_waitcnt vmcnt(1)
	v_lshlrev_b32_e32 v32, 16, v31
	v_and_b32_e32 v33, 0xffff0000, v31
	v_lshlrev_b32_e32 v38, 16, v26
	v_and_b32_e32 v39, 0xffff0000, v26
	v_lshlrev_b32_e32 v26, 16, v30
	v_and_b32_e32 v27, 0xffff0000, v30
	v_pk_add_f32 v[32:33], v[18:19], v[32:33]
	s_waitcnt vmcnt(0)
	v_lshlrev_b32_e32 v18, 16, v37
	v_and_b32_e32 v19, 0xffff0000, v37
	v_pk_add_f32 v[44:45], v[38:39], v[26:27]
	v_lshlrev_b32_e32 v42, 16, v36
	v_and_b32_e32 v43, 0xffff0000, v36
	v_lshlrev_b32_e32 v38, 16, v35
	v_and_b32_e32 v39, 0xffff0000, v35
	v_lshlrev_b32_e32 v46, 16, v34
	v_and_b32_e32 v47, 0xffff0000, v34
	global_load_dwordx4 v[34:37], v[20:21], off offset:3072
	global_load_dwordx4 v[50:53], v[22:23], off offset:3072
	s_nop 0
	global_load_dwordx4 v[54:57], v[54:55], off offset:3072
	v_lshlrev_b32_e32 v26, 16, v25
	v_and_b32_e32 v27, 0xffff0000, v25
	v_lshlrev_b32_e32 v30, 16, v29
	v_and_b32_e32 v31, 0xffff0000, v29
	v_pk_add_f32 v[40:41], v[26:27], v[30:31]
	v_lshlrev_b32_e32 v26, 16, v24
	v_and_b32_e32 v27, 0xffff0000, v24
	v_lshlrev_b32_e32 v24, 16, v28
	v_and_b32_e32 v25, 0xffff0000, v28
	v_pk_add_f32 v[48:49], v[26:27], v[24:25]
	v_pk_mul_f32 v[68:69], v[40:41], v[40:41]
	v_pk_mul_f32 v[66:67], v[44:45], v[44:45]
	v_pk_mul_f32 v[64:65], v[32:33], v[32:33]
	s_waitcnt vmcnt(2)
	v_lshlrev_b32_e32 v20, 16, v37
	v_and_b32_e32 v21, 0xffff0000, v37
	v_lshlrev_b32_e32 v24, 16, v36
	v_and_b32_e32 v25, 0xffff0000, v36
	v_lshlrev_b32_e32 v28, 16, v35
	v_and_b32_e32 v29, 0xffff0000, v35
	v_lshlrev_b32_e32 v36, 16, v34
	v_and_b32_e32 v37, 0xffff0000, v34
	s_waitcnt vmcnt(1)
	v_lshlrev_b32_e32 v34, 16, v50
	v_and_b32_e32 v35, 0xffff0000, v50
	v_lshlrev_b32_e32 v30, 16, v51
	v_and_b32_e32 v31, 0xffff0000, v51
	v_pk_add_f32 v[36:37], v[36:37], v[34:35]
	v_lshlrev_b32_e32 v22, 16, v53
	v_and_b32_e32 v23, 0xffff0000, v53
	v_lshlrev_b32_e32 v26, 16, v52
	v_and_b32_e32 v27, 0xffff0000, v52
	v_pk_add_f32 v[30:31], v[28:29], v[30:31]
	s_waitcnt vmcnt(0)
	v_lshlrev_b32_e32 v28, 16, v55
	v_and_b32_e32 v29, 0xffff0000, v55
	v_lshlrev_b32_e32 v34, 16, v54
	v_and_b32_e32 v35, 0xffff0000, v54
	v_mov_b32_e32 v54, v37
	v_mov_b32_e32 v55, v49
	v_pk_add_f32 v[22:23], v[20:21], v[22:23]
	v_lshlrev_b32_e32 v20, 16, v57
	v_and_b32_e32 v21, 0xffff0000, v57
	v_pk_add_f32 v[26:27], v[24:25], v[26:27]
	v_lshlrev_b32_e32 v24, 16, v56
	v_and_b32_e32 v25, 0xffff0000, v56
	v_pk_mul_f32 v[56:57], v[30:31], v[30:31]
	v_mov_b32_e32 v50, v36
	v_mov_b32_e32 v51, v48
	v_pk_mul_f32 v[54:55], v[54:55], v[54:55]
	v_pk_mul_f32 v[52:53], v[26:27], v[26:27]
	v_pk_fma_f32 v[50:51], v[50:51], v[50:51], v[54:55]
	v_mov_b32_e32 v54, v56
	v_mov_b32_e32 v55, v68
	v_pk_add_f32 v[50:51], v[54:55], v[50:51]
	v_mov_b32_e32 v68, v57
	v_pk_add_f32 v[50:51], v[68:69], v[50:51]
	v_mov_b32_e32 v54, v52
	v_mov_b32_e32 v55, v66
	v_pk_mul_f32 v[70:71], v[22:23], v[22:23]
	v_pk_add_f32 v[50:51], v[54:55], v[50:51]
	v_mov_b32_e32 v66, v53
	v_pk_add_f32 v[50:51], v[66:67], v[50:51]
	v_mov_b32_e32 v52, v70
	v_mov_b32_e32 v53, v64
	v_pk_add_f32 v[50:51], v[52:53], v[50:51]
	v_mov_b32_e32 v64, v71
	v_pk_add_f32 v[50:51], v[64:65], v[50:51]
	ds_bpermute_b32 v53, v58, v51
	ds_bpermute_b32 v52, v58, v50
	s_waitcnt lgkmcnt(0)
	v_pk_add_f32 v[50:51], v[50:51], v[52:53]
	ds_bpermute_b32 v53, v59, v51
	ds_bpermute_b32 v52, v59, v50
	s_waitcnt lgkmcnt(0)
	v_pk_add_f32 v[50:51], v[50:51], v[52:53]
	ds_bpermute_b32 v53, v60, v51
	ds_bpermute_b32 v52, v60, v50
	s_waitcnt lgkmcnt(0)
	v_pk_add_f32 v[50:51], v[50:51], v[52:53]
	ds_bpermute_b32 v53, v61, v51
	ds_bpermute_b32 v52, v61, v50
	s_waitcnt lgkmcnt(0)
	v_pk_add_f32 v[50:51], v[50:51], v[52:53]
	s_nop 0
	v_pk_fma_f32 v[16:17], v[50:51], s[10:11], v[16:17] op_sel_hi:[1,0,0]
	s_nop 0
	v_mul_f32_e32 v50, 0x4b800000, v17
	v_cmp_gt_f32_e64 s[10:11], s72, v17
	v_cmp_gt_f32_e32 vcc, s72, v16
	s_nop 0
	v_cndmask_b32_e64 v17, v17, v50, s[10:11]
	v_rsq_f32_e32 v17, v17
	s_nop 0
	v_mul_f32_e32 v50, 0x45800000, v17
	v_cndmask_b32_e64 v50, v17, v50, s[10:11]
	v_pk_mul_f32 v[44:45], v[44:45], v[50:51] op_sel_hi:[1,0]
	v_pk_mul_f32 v[48:49], v[48:49], v[50:51] op_sel_hi:[1,0]
	v_pk_mul_f32 v[0:1], v[108:109], v[44:45]
	v_pk_mul_f32 v[4:5], v[112:113], v[48:49]
	v_pk_mul_f32 v[42:43], v[0:1], v[42:43]
	v_pk_mul_f32 v[0:1], v[40:41], v[50:51] op_sel_hi:[1,0]
	v_pk_mul_f32 v[4:5], v[4:5], v[46:47]
	v_pk_mul_f32 v[0:1], v[114:115], v[0:1]
	v_mul_f32_e32 v17, 0x4b800000, v16
	v_pk_mul_f32 v[6:7], v[0:1], v[38:39]
	v_pk_mul_f32 v[0:1], v[32:33], v[50:51] op_sel_hi:[1,0]
	v_cndmask_b32_e32 v16, v16, v17, vcc
	v_pk_mul_f32 v[0:1], v[110:111], v[0:1]
	v_cvt_pk_bf16_f32 v2, v42, v43
	v_pk_mul_f32 v[18:19], v[0:1], v[18:19]
	v_cvt_pk_bf16_f32 v0, v4, v5
	v_cvt_pk_bf16_f32 v1, v6, v7
	v_cvt_pk_bf16_f32 v3, v18, v19
	global_store_dwordx4 v[14:15], v[0:3], off offset:2048
	s_nop 0
	v_rsq_f32_e32 v16, v16
	s_nop 0
	v_mul_f32_e32 v17, 0x45800000, v16
	v_cndmask_b32_e32 v16, v16, v17, vcc
	v_pk_mul_f32 v[18:19], v[36:37], v[16:17] op_sel_hi:[1,0]
	v_pk_mul_f32 v[4:5], v[112:113], v[18:19]
	v_pk_mul_f32 v[18:19], v[26:27], v[16:17] op_sel_hi:[1,0]
	v_pk_mul_f32 v[4:5], v[4:5], v[34:35]
	v_pk_mul_f32 v[0:1], v[108:109], v[18:19]
	s_nop 0
	v_pk_mul_f32 v[18:19], v[0:1], v[24:25]
	v_pk_mul_f32 v[0:1], v[30:31], v[16:17] op_sel_hi:[1,0]
	s_nop 0
	v_pk_mul_f32 v[0:1], v[114:115], v[0:1]
	s_nop 0
	v_pk_mul_f32 v[6:7], v[0:1], v[28:29]
	v_pk_mul_f32 v[0:1], v[22:23], v[16:17] op_sel_hi:[1,0]
	s_nop 0
	v_pk_mul_f32 v[0:1], v[110:111], v[0:1]
	v_cvt_pk_bf16_f32 v2, v18, v19
	v_pk_mul_f32 v[16:17], v[0:1], v[20:21]
	v_cvt_pk_bf16_f32 v0, v4, v5
	v_cvt_pk_bf16_f32 v1, v6, v7
	v_cvt_pk_bf16_f32 v3, v16, v17
	global_store_dwordx4 v[14:15], v[0:3], off offset:3072
	s_cbranch_scc1 .LBB0_721
